# attention dispatch order: stick-breaking units before chunk units (longer units first, shorter tail); plus fox skip threshold 93 nats (exact)
# speedup vs baseline: 1.0059x; 1.0059x over previous
; template <int MODE>
; __device__ __forceinline__ void attn_unit(const AttnArgs& A, int b, int head, int ub, ALAS unsigned char* lds) {
;     ...
;     const int skey = tid >> 3, sc8 = tid & 7;
;     u32x4 kreg, vreg; float cb = 0.f;
;     ...
;     u32x4 kp_[4], vp_[4]; float cbp_[4] = {0.f, 0.f, 0.f, 0.f};
; #pragma unroll
;     for (int i = 0; i < 4; ++i) { const bf16_t* src_ = A.P + (rowbase + 64 * (jt_hi - i) + skey) * LDP + 8 * sc8; kp_[i] = *(const u32x4*)(src_ + kcol); vp_[i] = *(const u32x4*)(src_ + vcol);
;         if (MODE == 2 && tid < 64) cbp_[i] = A.cum[(size_t)bh * SEQ + 64 * (jt_hi - i) + tid]; }
;     u32x4 gate4_[2][2];
;     { const bf16_t* grow_ = A.P + (rowbase + trow) * LDP + gcol + 8 * h;
; #pragma unroll
;       for (int db = 0; db < 2; ++db)
; #pragma unroll
;           for (int gq = 0; gq < 2; ++gq) gate4_[db][gq] = *(const u32x4*)(grow_ + 32 * db + 16 * gq); }
; __device__ __forceinline__ void attn_phase(const AttnArgs& A, ALAS unsigned char* lds) {
;     ...
;         const int y = got / NQ_PER, e = got % NQ_PER;
;         if (e < 256) { const int pair = e >> 5, wi = e & 31; attn_unit<2>(A, 2 * pair + (wi & 1), y, 15 - (wi >> 1), lds); }
;         else if (e < 512) { const int e2 = e - 256; attn_unit<1>(A, e2 >> 4, y, 15 - (e2 & 15), lds); }
;         else { const int e2 = e - 512; attn_unit<0>(A, e2 >> 4, y, 15 - (e2 & 15), lds); }
.LBB0_321:
	s_or_b64 exec, exec, s[2:3]
	s_mul_hi_u32 s1, s0, 0xaaaaaaab
	s_lshr_b32 s19, s1, 9
	s_mul_i32 s1, s19, 0x300
	s_sub_i32 s33, s0, s1
	s_cmpk_gt_u32 s33, 0xff
	s_mov_b64 s[2:3], -1
	s_cbranch_scc0 .LBB0_386
	s_and_b32 s1, s33, 15
	s_xor_b32 s16, s1, 15
	s_cmpk_gt_u32 s33, 0x1ff
	s_cbranch_scc1 .LBB0_374
	v_mov_b32_e32 v26, v188
	s_lshl_b32 s3, s33, 8
	v_readfirstlane_b32 s0, v26
	s_ashr_i32 s6, s0, 6
	s_lshl_b32 s28, s16, 2
	s_lshl_b32 s2, s16, 8
	s_and_b32 s3, s3, 0x1f000
	s_lshl_b32 s4, s6, 5
	s_or_b32 s10, s28, 3
	s_add_i32 s3, s3, 0xffff0000
	s_add_i32 s7, s4, s2
	v_ashrrev_i32_e32 v20, 3, v26
	v_and_b32_e32 v29, 7, v26
	s_lshl_b32 s4, s10, 6
	v_ashrrev_i32_e32 v21, 31, v20
	v_lshlrev_b32_e32 v0, 4, v29
	s_or_b32 s24, s4, s3
	v_lshl_add_u64 v[18:19], s[82:83], 0, v[0:1]
	v_lshl_add_u64 v[2:3], v[20:21], 0, s[24:25]
	v_mad_u64_u32 v[4:5], s[4:5], v2, s34, v[18:19]
	v_mad_i32_i24 v5, v3, s34, v5
	s_lshl_b32 s4, s19, 7
	s_mov_b32 s5, s25
	s_or_b32 s29, s28, 2
	v_lshl_add_u64 v[2:3], v[4:5], 0, s[4:5]
	s_movk_i32 s14, 0x1000
	s_lshl_b32 s8, s29, 6
	v_add_co_u32_e32 v4, vcc, s14, v2
	s_or_b32 s24, s8, s3
	s_nop 0
	v_addc_co_u32_e32 v5, vcc, 0, v3, vcc
	global_load_dwordx4 v[30:33], v[2:3], off offset:3072
	global_load_dwordx4 v[34:37], v[4:5], off offset:2048
	v_lshl_add_u64 v[2:3], v[20:21], 0, s[24:25]
	v_mad_u64_u32 v[4:5], s[8:9], v2, s34, v[18:19]
	v_mad_i32_i24 v5, v3, s34, v5
	s_or_b32 s11, s28, 1
	v_lshl_add_u64 v[2:3], v[4:5], 0, s[4:5]
	s_lshl_b32 s8, s11, 6
	v_add_co_u32_e32 v4, vcc, s14, v2
	s_or_b32 s24, s8, s3
	s_nop 0
	v_addc_co_u32_e32 v5, vcc, 0, v3, vcc
	global_load_dwordx4 v[38:41], v[2:3], off offset:3072
	global_load_dwordx4 v[42:45], v[4:5], off offset:2048
	v_lshl_add_u64 v[2:3], v[20:21], 0, s[24:25]
	v_mad_u64_u32 v[4:5], s[8:9], v2, s34, v[18:19]
	v_mad_i32_i24 v5, v3, s34, v5
	v_lshl_add_u64 v[2:3], v[4:5], 0, s[4:5]
	v_add_co_u32_e32 v4, vcc, s14, v2
	s_or_b32 s24, s2, s3
	s_nop 0
	v_addc_co_u32_e32 v5, vcc, 0, v3, vcc
	global_load_dwordx4 v[46:49], v[2:3], off offset:3072
	global_load_dwordx4 v[50:53], v[4:5], off offset:2048
	v_lshl_add_u64 v[2:3], v[20:21], 0, s[24:25]
	v_mad_u64_u32 v[4:5], s[8:9], v2, s34, v[18:19]
	v_mad_i32_i24 v5, v3, s34, v5
	v_and_b32_e32 v28, 31, v26
	v_lshl_add_u64 v[2:3], v[4:5], 0, s[4:5]
	v_add_co_u32_e32 v4, vcc, s14, v2
	v_or_b32_e32 v22, s7, v28
	s_nop 0
	v_addc_co_u32_e32 v5, vcc, 0, v3, vcc
	s_mov_b32 s24, s3
	v_ashrrev_i32_e32 v23, 31, v22
	global_load_dwordx4 v[128:131], v[2:3], off offset:3072
	global_load_dwordx4 v[132:135], v[4:5], off offset:2048
	v_lshl_add_u64 v[2:3], v[22:23], 0, s[24:25]
	v_mov_b64_e32 v[4:5], s[82:83]
	v_mad_u64_u32 v[4:5], s[8:9], v2, s34, v[4:5]
	v_bfe_u32 v27, v26, 5, 1
	v_mad_i32_i24 v5, v3, s34, v5
	v_lshl_add_u64 v[2:3], v[4:5], 0, s[4:5]
	v_lshlrev_b32_e32 v24, 4, v27
	v_mov_b32_e32 v25, v1
	v_lshl_add_u64 v[152:153], v[2:3], 0, v[24:25]
	s_mov_b64 s[4:5], 0x2400
	v_add_co_u32_e32 v4, vcc, s30, v152
	v_lshl_add_u64 v[2:3], v[152:153], 0, s[4:5]
	s_nop 0
	v_addc_co_u32_e32 v5, vcc, 0, v153, vcc
	global_load_dwordx4 v[120:123], v[2:3], off offset:32
	global_load_dwordx4 v[116:119], v[2:3], off offset:64
	global_load_dwordx4 v[124:127], v[4:5], off offset:1024
	global_load_dwordx4 v[112:115], v[2:3], off offset:96
	global_load_dwordx4 v[14:17], v[152:153], off
	global_load_dwordx4 v[10:13], v[152:153], off offset:32
	global_load_dwordx4 v[6:9], v[152:153], off offset:64
	s_nop 0
	global_load_dwordx4 v[2:5], v[152:153], off offset:96
	s_mul_i32 s3, s10, 43
	s_lshr_b32 s3, s3, 8
	s_mul_i32 s3, s3, 6
	s_sub_i32 s3, s10, s3
	v_mul_lo_u32 v23, v20, s31
	s_and_b32 s3, s3, 0xff
	s_waitcnt vmcnt(20)
	v_add3_u32 v160, 0, v23, v0
	s_mulk_i32 s3, 0x2400
	v_add_u32_e32 v0, s3, v160
	s_mul_i32 s3, s29, 43
	s_lshr_b32 s3, s3, 8
	s_mul_i32 s3, s3, 6
	s_sub_i32 s3, s29, s3
	s_and_b32 s3, s3, 0xfe
	s_mulk_i32 s3, 0x2400
	s_waitcnt vmcnt(15)
	ds_write_b128 v0, v[30:33]
	s_waitcnt vmcnt(14)
	ds_write_b128 v0, v[34:37] offset:55296
	v_add_u32_e32 v0, s3, v160
	s_mul_i32 s3, s11, 43
	s_lshr_b32 s3, s3, 8
	s_mul_i32 s3, s3, 6
	s_sub_i32 s3, s11, s3
	s_and_b32 s3, s3, 0xff
	s_mulk_i32 s3, 0x2400
	s_waitcnt vmcnt(13)
	ds_write_b128 v0, v[38:41]
	s_waitcnt vmcnt(12)
	ds_write_b128 v0, v[42:45] offset:55296
	v_add_u32_e32 v0, s3, v160
	s_mul_i32 s3, s16, 0xac
	s_lshr_b32 s3, s3, 8
	s_mul_i32 s3, s3, 6
	s_sub_i32 s3, s28, s3
	s_and_b32 s3, s3, 0xfe
	s_lshl_b32 s14, s19, 6
	s_mulk_i32 s3, 0x2400
	s_waitcnt vmcnt(11)
	ds_write_b128 v0, v[46:49]
	s_waitcnt vmcnt(10)
	ds_write_b128 v0, v[50:53] offset:55296
	v_add_u32_e32 v0, s3, v160
	s_cmp_eq_u32 s1, 15
	s_waitcnt vmcnt(9)
	ds_write_b128 v0, v[128:131]
	s_waitcnt vmcnt(8)
	ds_write_b128 v0, v[132:135] offset:55296
	s_cbranch_scc1 .LBB0_325
	s_add_i32 s2, s2, s24
	s_sub_i32 s2, s2, 64
	s_mov_b32 s3, s25
	v_lshl_add_u64 v[30:31], s[2:3], 0, v[20:21]
	v_mov_b64_e32 v[32:33], s[82:83]
	v_lshlrev_b32_e32 v0, 3, v29
	v_mad_u64_u32 v[32:33], s[2:3], v30, s34, v[32:33]
	v_mad_i32_i24 v33, v31, s34, v33
	v_lshlrev_b32_e32 v0, 1, v0
	v_lshl_add_u64 v[30:31], v[32:33], 0, v[0:1]
	s_lshl_b32 s2, s14, 1
	s_mov_b32 s3, s25
	v_lshl_add_u64 v[30:31], v[30:31], 0, s[2:3]
	v_add_co_u32_e32 v32, vcc, 0x1000, v30
	s_nop 1
	v_addc_co_u32_e32 v33, vcc, 0, v31, vcc
	global_load_dwordx4 v[128:131], v[30:31], off offset:3072
	global_load_dwordx4 v[132:135], v[32:33], off offset:2048

; template <int MODE>
; __device__ __forceinline__ void attn_unit(const AttnArgs& A, int b, int head, int ub, ALAS unsigned char* lds) {
;     ...
;     u32x4 kp_[4], vp_[4]; float cbp_[4] = {0.f, 0.f, 0.f, 0.f};
; #pragma unroll
;     for (int i = 0; i < 4; ++i) { const bf16_t* src_ = A.P + (rowbase + 64 * (jt_hi - i) + skey) * LDP + 8 * sc8; kp_[i] = *(const u32x4*)(src_ + kcol); vp_[i] = *(const u32x4*)(src_ + vcol);
;         if (MODE == 2 && tid < 64) cbp_[i] = A.cum[(size_t)bh * SEQ + 64 * (jt_hi - i) + tid]; }
;     u32x4 gate4_[2][2];
;     { const bf16_t* grow_ = A.P + (rowbase + trow) * LDP + gcol + 8 * h;
; #pragma unroll
;       for (int db = 0; db < 2; ++db)
; #pragma unroll
;           for (int gq = 0; gq < 2; ++gq) gate4_[db][gq] = *(const u32x4*)(grow_ + 32 * db + 16 * gq); }
;     bf16x8 qf[4];
;     float qkb = 0.f;
;     {
;         const bf16_t* qp = A.P + (rowbase + trow) * LDP + qcol + 8 * h;
;         float qv[4][8];
; #pragma unroll
;         for (int st = 0; st < 4; ++st) { const u32x4 raw = *(const u32x4*)(qp + 16 * st);
; #pragma unroll
;             for (int i = 0; i < 4; ++i) { qv[st][2 * i] = bflo(raw[i]); qv[st][2 * i + 1] = bfhi(raw[i]); } }
;         if (MODE != 0) {
;             float ss = 0.f;
; #pragma unroll
;             for (int st = 0; st < 4; ++st)
; #pragma unroll
;                 for (int j = 0; j < 8; ++j) ss += qv[st][j] * qv[st][j];
;             ss += __shfl_xor(ss, 32);
;             const float sc = __builtin_amdgcn_rsqf(ss * (1.0f / 64.0f) + 1e-6f) * QSCALE;
;             const float* gq = (MODE == 1) ? A.gq_ch : A.gq_fx; const float* gk = (MODE == 1) ? A.gk_ch : A.gk_fx;
;             float qn = 0.f;
; #pragma unroll
;             for (int st = 0; st < 4; ++st) { const f32x4 a0 = *(const f32x4*)(gq + 16 * st + 8 * h), a1 = *(const f32x4*)(gq + 16 * st + 8 * h + 4);
;                 const f32x4 b0 = *(const f32x4*)(gk + 16 * st + 8 * h), b1 = *(const f32x4*)(gk + 16 * st + 8 * h + 4);
; #pragma unroll
;                 for (int j = 0; j < 4; ++j) { qv[st][j] *= sc * a0[j] * b0[j]; qv[st][4 + j] *= sc * a1[j] * b1[j]; qn += qv[st][j] * qv[st][j] + qv[st][4 + j] * qv[st][4 + j]; } }
; __device__ __forceinline__ void attn_phase(const AttnArgs& A, ALAS unsigned char* lds) {
;     ...
;         else if (e < 512) { const int e2 = e - 256; attn_unit<1>(A, e2 >> 4, y, 15 - (e2 & 15), lds); }
.LBB0_374:
	s_and_b64 vcc, exec, s[2:3]
	s_cbranch_vccz .LBB0_385
	s_waitcnt vmcnt(5)
	v_mov_b32_e32 v128, v188
	s_lshl_b32 s0, s33, 8
	v_readfirstlane_b32 s1, v128
	s_and_b32 s0, s0, 0x3f000
	s_ashr_i32 s22, s1, 1
	s_lshl_b32 s6, s16, 8
	s_add_i32 s2, s0, 0xfffe0000
	s_and_b32 s0, s22, 0xffffffe0
	s_add_i32 s3, s0, s6
	s_lshl_b32 s0, s16, 2
	s_or_b32 s9, s0, 3
	v_ashrrev_i32_e32 v94, 3, v128
	s_lshl_b32 s4, s9, 6
	s_or_b32 s8, s0, 2
	v_ashrrev_i32_e32 v95, 31, v94
	s_or_b32 s24, s4, s2
	s_lshl_b32 s4, s8, 6
	s_or_b32 s7, s0, 1
	v_lshl_add_u64 v[2:3], v[94:95], 0, s[24:25]
	s_or_b32 s24, s4, s2
	s_lshl_b32 s4, s7, 6
	v_and_b32_e32 v221, 31, v128
	v_lshl_add_u64 v[4:5], v[94:95], 0, s[24:25]
	s_or_b32 s24, s4, s2
	v_lshl_add_u64 v[6:7], v[94:95], 0, s[24:25]
	s_or_b32 s24, s6, s2
	s_waitcnt vmcnt(1)
	v_or_b32_e32 v10, s3, v221
	v_lshl_add_u64 v[8:9], v[94:95], 0, s[24:25]
	s_mov_b32 s24, s2
	v_ashrrev_i32_e32 v11, 31, v10
	v_lshl_add_u64 v[10:11], v[10:11], 0, s[24:25]
	v_mov_b64_e32 v[12:13], s[82:83]
	v_mad_u64_u32 v[12:13], s[2:3], v10, s34, v[12:13]
	v_bfe_u32 v129, v128, 5, 1
	v_mad_i32_i24 v13, v11, s34, v13
	s_lshl_b32 s2, s19, 7
	s_mov_b32 s3, s25
	v_lshl_add_u64 v[10:11], v[12:13], 0, s[2:3]
	v_lshlrev_b32_e32 v96, 4, v129
	v_mov_b32_e32 v97, v1
	v_lshl_add_u64 v[202:203], v[10:11], 0, v[96:97]
	global_load_dwordx4 v[110:113], v[202:203], off offset:1120
	global_load_dwordx4 v[114:117], v[202:203], off offset:1088
	global_load_dwordx4 v[118:121], v[202:203], off offset:1024
	global_load_dwordx4 v[122:125], v[202:203], off offset:1056
	v_and_b32_e32 v97, 7, v128
	v_lshlrev_b32_e32 v0, 4, v97
	s_lshl_b32 s2, s19, 6
	v_lshl_add_u64 v[30:31], s[82:83], 0, v[0:1]
	s_add_i32 s4, s2, 0x800
	s_add_i32 s5, s2, 0xe00
	v_mad_u64_u32 v[10:11], s[2:3], v2, s34, v[30:31]
	v_mad_i32_i24 v11, v3, s34, v11
	s_lshl_b32 s40, s4, 1
	s_mov_b32 s41, s25
	v_lshl_add_u64 v[2:3], v[10:11], 0, s[40:41]
	s_lshl_b32 s10, s5, 1
	s_mov_b32 s11, s25
	v_lshl_add_u64 v[10:11], v[10:11], 0, s[10:11]
	global_load_dwordx4 v[26:29], v[2:3], off
	global_load_dwordx4 v[18:21], v[10:11], off
	v_mad_u64_u32 v[2:3], s[2:3], v4, s34, v[30:31]
	v_mad_i32_i24 v3, v5, s34, v3
	v_lshl_add_u64 v[4:5], v[2:3], 0, s[40:41]
	v_lshl_add_u64 v[2:3], v[2:3], 0, s[10:11]
	global_load_dwordx4 v[22:25], v[4:5], off
	global_load_dwordx4 v[10:13], v[2:3], off
	v_mad_u64_u32 v[2:3], s[2:3], v6, s34, v[30:31]
	v_mad_i32_i24 v3, v7, s34, v3
	v_mad_u64_u32 v[6:7], s[2:3], v8, s34, v[30:31]
	s_mov_b64 s[2:3], 0x2800
	v_mad_i32_i24 v7, v9, s34, v7
	v_lshl_add_u64 v[126:127], v[202:203], 0, s[2:3]
	v_readlane_b32 s2, v248, 28
	v_lshl_add_u64 v[4:5], v[2:3], 0, s[40:41]
	v_lshl_add_u64 v[2:3], v[2:3], 0, s[10:11]
	v_lshl_add_u64 v[8:9], v[6:7], 0, s[40:41]
	v_and_b32_e32 v38, 32, v128
	v_readlane_b32 s3, v248, 29
	global_load_dwordx4 v[14:17], v[4:5], off
	s_nop 0
	global_load_dwordx4 v[2:5], v[2:3], off
	v_lshl_add_u64 v[30:31], v[6:7], 0, s[10:11]
	global_load_dwordx4 v[6:9], v[8:9], off
	s_nop 0
	global_load_dwordx4 v[160:163], v[30:31], off
	global_load_dwordx4 v[82:85], v38, s[2:3]
	global_load_dwordx4 v[78:81], v38, s[2:3] offset:16
	v_and_b32_e32 v31, 64, v214
	v_xor_b32_e32 v30, 32, v214
	v_add_u32_e32 v108, 64, v31
	v_cmp_lt_i32_e32 vcc, v30, v108
	v_readlane_b32 s4, v248, 30
	v_readlane_b32 s5, v248, 31
	v_cndmask_b32_e32 v30, v214, v30, vcc
	v_lshlrev_b32_e32 v216, 2, v30
	s_nop 2
	global_load_dwordx4 v[90:93], v38, s[4:5]
	global_load_dwordx4 v[86:89], v38, s[4:5] offset:16
	global_load_dwordx4 v[70:73], v38, s[2:3] offset:64
	global_load_dwordx4 v[62:65], v38, s[2:3] offset:80
	global_load_dwordx4 v[74:77], v38, s[4:5] offset:64
	global_load_dwordx4 v[66:69], v38, s[4:5] offset:80
	global_load_dwordx4 v[54:57], v38, s[2:3] offset:128
	global_load_dwordx4 v[46:49], v38, s[2:3] offset:144
	global_load_dwordx4 v[58:61], v38, s[4:5] offset:128
	global_load_dwordx4 v[50:53], v38, s[4:5] offset:144
	global_load_dwordx4 v[34:37], v38, s[2:3] offset:192
	global_load_dwordx4 v[30:33], v38, s[2:3] offset:208
	global_load_dwordx4 v[42:45], v38, s[4:5] offset:192
	s_nop 0
	global_load_dwordx4 v[38:41], v38, s[4:5] offset:208
	v_and_b32_e32 v109, 63, v128
	s_mul_i32 s2, s19, 0x101
	s_mov_b32 s3, 0xf149f2ca
	s_waitcnt vmcnt(27)
	v_lshlrev_b32_e32 v104, 16, v110
	s_waitcnt vmcnt(25)
	v_lshlrev_b32_e32 v178, 16, v118
	v_and_b32_e32 v179, 0xffff0000, v118
	v_lshlrev_b32_e32 v176, 16, v119
	v_and_b32_e32 v177, 0xffff0000, v119
	v_pk_mul_f32 v[118:119], v[178:179], v[178:179]
	v_pk_mul_f32 v[150:151], v[176:177], v[176:177]
	v_add_f32_e32 v118, v118, v119
	v_lshlrev_b32_e32 v174, 16, v120
	v_and_b32_e32 v175, 0xffff0000, v120
	v_add_f32_e32 v118, v150, v118
	v_lshlrev_b32_e32 v172, 16, v121
	v_and_b32_e32 v173, 0xffff0000, v121
	v_pk_mul_f32 v[120:121], v[174:175], v[174:175]
	v_add_f32_e32 v118, v151, v118
	v_add_f32_e32 v118, v120, v118
	v_pk_mul_f32 v[148:149], v[172:173], v[172:173]
	v_add_f32_e32 v118, v121, v118
	s_waitcnt vmcnt(24)
; template <int MODE>
; __device__ __forceinline__ void attn_unit(const AttnArgs& A, int b, int head, int ub, ALAS unsigned char* lds) {
;     ...
;             float ss = 0.f;
; #pragma unroll
;             for (int st = 0; st < 4; ++st)
; #pragma unroll
;                 for (int j = 0; j < 8; ++j) ss += qv[st][j] * qv[st][j];
;             ss += __shfl_xor(ss, 32);
;             const float sc = __builtin_amdgcn_rsqf(ss * (1.0f / 64.0f) + 1e-6f) * QSCALE;
;             const float* gq = (MODE == 1) ? A.gq_ch : A.gq_fx; const float* gk = (MODE == 1) ? A.gk_ch : A.gk_fx;
;             float qn = 0.f;
; #pragma unroll
;             for (int st = 0; st < 4; ++st) { const f32x4 a0 = *(const f32x4*)(gq + 16 * st + 8 * h), a1 = *(const f32x4*)(gq + 16 * st + 8 * h + 4);
;                 const f32x4 b0 = *(const f32x4*)(gk + 16 * st + 8 * h), b1 = *(const f32x4*)(gk + 16 * st + 8 * h + 4);
; #pragma unroll
;                 for (int j = 0; j < 4; ++j) { qv[st][j] *= sc * a0[j] * b0[j]; qv[st][4 + j] *= sc * a1[j] * b1[j]; qn += qv[st][j] * qv[st][j] + qv[st][4 + j] * qv[st][4 + j]; } }
;             qn += __shfl_xor(qn, 32);
;             qkb = __builtin_sqrtf(qn) * 8.1f;
;     ...
;         float rbm = NEG_BIG;
; #pragma unroll
;         for (int i = 0; i < 5; ++i) { const int e = lane + 64 * i; if (e < 257) rbm = fmaxf(rbm, A.relb[head * 257 + e]); }
; #pragma unroll
;         for (int o = 1; o < 64; o <<= 1) rbm = fmaxf(rbm, __shfl_xor(rbm, o));
	v_lshlrev_b32_e32 v170, 16, v122
	v_and_b32_e32 v171, 0xffff0000, v122
	v_add_f32_e32 v118, v148, v118
	v_lshlrev_b32_e32 v168, 16, v123
	v_and_b32_e32 v169, 0xffff0000, v123
	v_pk_mul_f32 v[122:123], v[170:171], v[170:171]
	v_add_f32_e32 v118, v149, v118
	v_add_f32_e32 v118, v122, v118
	v_pk_mul_f32 v[146:147], v[168:169], v[168:169]
	v_add_f32_e32 v118, v123, v118
	v_lshlrev_b32_e32 v166, 16, v124
	v_and_b32_e32 v167, 0xffff0000, v124
	v_add_f32_e32 v118, v146, v118
	v_lshlrev_b32_e32 v164, 16, v125
	v_and_b32_e32 v165, 0xffff0000, v125
	v_pk_mul_f32 v[124:125], v[166:167], v[166:167]
	v_add_f32_e32 v118, v147, v118
	v_add_f32_e32 v118, v124, v118
	v_pk_mul_f32 v[144:145], v[164:165], v[164:165]
	v_add_f32_e32 v118, v125, v118
	v_lshlrev_b32_e32 v142, 16, v114
	v_and_b32_e32 v143, 0xffff0000, v114
	v_add_f32_e32 v118, v144, v118
	v_lshlrev_b32_e32 v138, 16, v115
	v_and_b32_e32 v139, 0xffff0000, v115
	v_pk_mul_f32 v[114:115], v[142:143], v[142:143]
	v_add_f32_e32 v118, v145, v118
	v_add_f32_e32 v114, v114, v118
	v_pk_mul_f32 v[140:141], v[138:139], v[138:139]
	v_add_f32_e32 v114, v115, v114
	v_lshlrev_b32_e32 v136, 16, v116
	v_and_b32_e32 v137, 0xffff0000, v116
	v_add_f32_e32 v114, v140, v114
	v_lshlrev_b32_e32 v106, 16, v117
	v_and_b32_e32 v107, 0xffff0000, v117
	v_pk_mul_f32 v[116:117], v[136:137], v[136:137]
	v_add_f32_e32 v114, v141, v114
	v_add_f32_e32 v114, v116, v114
	v_pk_mul_f32 v[134:135], v[106:107], v[106:107]
	v_add_f32_e32 v114, v117, v114
	v_and_b32_e32 v105, 0xffff0000, v110
	v_add_f32_e32 v114, v134, v114
	v_lshlrev_b32_e32 v102, 16, v111
	v_and_b32_e32 v103, 0xffff0000, v111
	v_pk_mul_f32 v[110:111], v[104:105], v[104:105]
	v_add_f32_e32 v114, v135, v114
	v_add_f32_e32 v110, v110, v114
	v_pk_mul_f32 v[132:133], v[102:103], v[102:103]
	v_add_f32_e32 v110, v111, v110
	v_lshlrev_b32_e32 v100, 16, v112
	v_and_b32_e32 v101, 0xffff0000, v112
	v_add_f32_e32 v110, v132, v110
	v_lshlrev_b32_e32 v98, 16, v113
	v_and_b32_e32 v99, 0xffff0000, v113
	v_pk_mul_f32 v[112:113], v[100:101], v[100:101]
	v_add_f32_e32 v110, v133, v110
	v_add_f32_e32 v110, v112, v110
	v_pk_mul_f32 v[130:131], v[98:99], v[98:99]
	v_add_f32_e32 v110, v113, v110
	v_add_f32_e32 v110, v130, v110
	v_add_f32_e32 v112, v131, v110
	ds_bpermute_b32 v113, v216, v112
	v_add_co_u32_e32 v110, vcc, s30, v202
	s_waitcnt lgkmcnt(0)
	v_add_f32_e32 v112, v112, v113
	v_fmamk_f32 v112, v112, 0x3c800000, v189
	v_rsq_f32_e32 v112, v112
	v_addc_co_u32_e32 v111, vcc, 0, v203, vcc
	global_load_dwordx4 v[152:155], v[126:127], off offset:32
	global_load_dwordx4 v[148:151], v[126:127], off offset:64
	global_load_dwordx4 v[156:159], v[110:111], off offset:2048
	global_load_dwordx4 v[144:147], v[126:127], off offset:96
	v_mul_f32_e32 v110, 0x3e38aa3b, v112
	s_waitcnt vmcnt(19)
	v_pk_mul_f32 v[82:83], v[82:83], v[110:111] op_sel_hi:[1,0]
	v_cmp_eq_u32_e32 vcc, 0, v109
	s_waitcnt vmcnt(17)
	v_pk_mul_f32 v[82:83], v[90:91], v[82:83]
	v_add_u32_e32 v90, s2, v109
	v_mov_b32_e32 v91, v1
	v_lshl_add_u64 v[90:91], v[90:91], 2, s[46:47]
	global_load_dword v111, v[90:91], off
	global_load_dword v112, v[90:91], off offset:256
	global_load_dword v113, v[90:91], off offset:512
	s_nop 0
	global_load_dword v90, v[90:91], off offset:768
	v_pk_mul_f32 v[82:83], v[82:83], v[178:179]
	s_waitcnt vmcnt(3)
	v_pk_mul_f32 v[78:79], v[78:79], v[110:111] op_sel_hi:[1,0]
	s_nop 0
	v_pk_mul_f32 v[78:79], v[86:87], v[78:79]
	v_pk_mul_f32 v[80:81], v[80:81], v[110:111] op_sel_hi:[1,0]
	v_pk_mul_f32 v[78:79], v[78:79], v[174:175]
	v_pk_mul_f32 v[84:85], v[84:85], v[110:111] op_sel_hi:[1,0]
	v_pk_mul_f32 v[80:81], v[88:89], v[80:81]
	v_pk_mul_f32 v[62:63], v[62:63], v[110:111] op_sel_hi:[1,0]
	v_pk_mul_f32 v[86:87], v[78:79], v[78:79]
	v_pk_mul_f32 v[84:85], v[92:93], v[84:85]
	v_pk_mul_f32 v[80:81], v[80:81], v[172:173]
	v_pk_mul_f32 v[70:71], v[70:71], v[110:111] op_sel_hi:[1,0]
	v_pk_mul_f32 v[62:63], v[66:67], v[62:63]
	v_pk_fma_f32 v[86:87], v[82:83], v[82:83], v[86:87]
	v_pk_mul_f32 v[84:85], v[84:85], v[176:177]
	v_pk_mul_f32 v[88:89], v[80:81], v[80:81]
	v_pk_mul_f32 v[70:71], v[74:75], v[70:71]
	v_pk_mul_f32 v[62:63], v[62:63], v[166:167]
	v_pk_mul_f32 v[34:35], v[34:35], v[110:111] op_sel_hi:[1,0]
	v_pk_fma_f32 v[88:89], v[84:85], v[84:85], v[88:89]
	v_pk_mul_f32 v[70:71], v[70:71], v[170:171]
	v_pk_mul_f32 v[66:67], v[62:63], v[62:63]
	v_pk_mul_f32 v[64:65], v[64:65], v[110:111] op_sel_hi:[1,0]
	v_pk_mul_f32 v[34:35], v[42:43], v[34:35]
	v_add_f32_e32 v42, v86, v87
	v_pk_fma_f32 v[74:75], v[70:71], v[70:71], v[66:67]
	v_pk_mul_f32 v[66:67], v[72:73], v[110:111] op_sel_hi:[1,0]
	v_pk_mul_f32 v[64:65], v[68:69], v[64:65]
	v_pk_mul_f32 v[46:47], v[46:47], v[110:111] op_sel_hi:[1,0]
	v_add_f32_e32 v42, v88, v42
	v_pk_mul_f32 v[66:67], v[76:77], v[66:67]
	v_pk_mul_f32 v[64:65], v[64:65], v[164:165]
	v_pk_mul_f32 v[54:55], v[54:55], v[110:111] op_sel_hi:[1,0]
	v_pk_mul_f32 v[46:47], v[50:51], v[46:47]
	v_add_f32_e32 v42, v89, v42
	v_pk_mul_f32 v[66:67], v[66:67], v[168:169]
	v_pk_mul_f32 v[68:69], v[64:65], v[64:65]
	v_pk_mul_f32 v[54:55], v[58:59], v[54:55]
	v_pk_mul_f32 v[46:47], v[46:47], v[136:137]
	v_add_f32_e32 v42, v74, v42
	v_pk_fma_f32 v[68:69], v[66:67], v[66:67], v[68:69]
	v_pk_mul_f32 v[54:55], v[54:55], v[142:143]
	v_pk_mul_f32 v[50:51], v[46:47], v[46:47]
	v_pk_mul_f32 v[48:49], v[48:49], v[110:111] op_sel_hi:[1,0]
	v_add_f32_e32 v42, v75, v42
	v_pk_fma_f32 v[58:59], v[54:55], v[54:55], v[50:51]
	v_pk_mul_f32 v[50:51], v[56:57], v[110:111] op_sel_hi:[1,0]
	v_pk_mul_f32 v[48:49], v[52:53], v[48:49]
	v_add_f32_e32 v42, v68, v42
	v_pk_mul_f32 v[50:51], v[60:61], v[50:51]
	v_pk_mul_f32 v[48:49], v[48:49], v[106:107]
	v_pk_mul_f32 v[30:31], v[30:31], v[110:111] op_sel_hi:[1,0]
	v_add_f32_e32 v42, v69, v42
	v_pk_mul_f32 v[50:51], v[50:51], v[138:139]
	v_pk_mul_f32 v[52:53], v[48:49], v[48:49]
	v_pk_mul_f32 v[30:31], v[38:39], v[30:31]
	v_add_f32_e32 v42, v58, v42
	v_pk_fma_f32 v[52:53], v[50:51], v[50:51], v[52:53]
	v_pk_mul_f32 v[30:31], v[30:31], v[100:101]
	v_pk_mul_f32 v[32:33], v[32:33], v[110:111] op_sel_hi:[1,0]
	v_add_f32_e32 v42, v59, v42
	v_pk_mul_f32 v[34:35], v[34:35], v[104:105]
	v_pk_mul_f32 v[38:39], v[30:31], v[30:31]
	v_pk_mul_f32 v[36:37], v[36:37], v[110:111] op_sel_hi:[1,0]
	v_pk_mul_f32 v[32:33], v[40:41], v[32:33]
	v_add_f32_e32 v42, v52, v42
	v_pk_fma_f32 v[38:39], v[34:35], v[34:35], v[38:39]
	v_pk_mul_f32 v[36:37], v[44:45], v[36:37]
	v_pk_mul_f32 v[32:33], v[32:33], v[98:99]
	v_add_f32_e32 v42, v53, v42
	v_pk_mul_f32 v[36:37], v[36:37], v[102:103]
	v_pk_mul_f32 v[40:41], v[32:33], v[32:33]
	v_add_f32_e32 v38, v38, v42
	v_pk_fma_f32 v[40:41], v[36:37], v[36:37], v[40:41]
	v_add_f32_e32 v38, v39, v38
	v_add_f32_e32 v38, v40, v38
	v_add_f32_e32 v38, v41, v38
	ds_bpermute_b32 v39, v216, v38
	s_waitcnt vmcnt(2)
	v_max3_f32 v40, v111, s3, v112
	s_waitcnt vmcnt(0)
	v_max3_f32 v40, v40, v113, v90
	s_and_saveexec_b64 s[4:5], vcc
	s_cbranch_execz .LBB0_377
; template <int MODE>
; __device__ __forceinline__ void attn_unit(const AttnArgs& A, int b, int head, int ub, ALAS unsigned char* lds) {
;     ...
;         for (int i = 0; i < 5; ++i) { const int e = lane + 64 * i; if (e < 257) rbm = fmaxf(rbm, A.relb[head * 257 + e]); }
	s_mov_b32 s3, s25
	s_lshl_b64 s[14:15], s[2:3], 2
	s_add_u32 s14, s46, s14
	s_addc_u32 s15, s47, s15
	global_load_dword v41, v1, s[14:15] offset:1024
	v_max_f32_e32 v40, v40, v40
	s_waitcnt vmcnt(0)
	v_max_f32_e32 v41, v41, v41
	v_max_f32_e32 v40, v40, v41
